# attention: softmax row sums accumulated with packed adds (34 instead of 64 VALU per step)
# baseline (speedup 1.0000x reference)
.LBB0_396:
	v_pk_add_f32 v[84:85], v[132:133], v[134:135]
	v_pk_add_f32 v[86:87], v[2:3], v[164:165]
	v_pk_add_f32 v[84:85], v[84:85], v[194:195]
	v_pk_add_f32 v[86:87], v[86:87], v[166:167]
	v_pk_add_f32 v[84:85], v[84:85], v[206:207]
	v_pk_add_f32 v[86:87], v[86:87], v[168:169]
	v_pk_add_f32 v[84:85], v[84:85], v[208:209]
	v_pk_add_f32 v[86:87], v[86:87], v[170:171]
	v_pk_add_f32 v[84:85], v[84:85], v[210:211]
	v_pk_add_f32 v[86:87], v[86:87], v[172:173]
	v_pk_add_f32 v[84:85], v[84:85], v[212:213]
	v_pk_add_f32 v[86:87], v[86:87], v[174:175]
	v_pk_add_f32 v[84:85], v[84:85], v[128:129]
	v_pk_add_f32 v[86:87], v[86:87], v[176:177]
	v_pk_add_f32 v[84:85], v[84:85], v[130:131]
	v_pk_add_f32 v[86:87], v[86:87], v[178:179]
	v_pk_add_f32 v[84:85], v[84:85], v[124:125]
	v_pk_add_f32 v[86:87], v[86:87], v[180:181]
	v_pk_add_f32 v[84:85], v[84:85], v[126:127]
	v_pk_add_f32 v[86:87], v[86:87], v[182:183]
	v_pk_add_f32 v[84:85], v[84:85], v[120:121]
	v_pk_add_f32 v[86:87], v[86:87], v[184:185]
	v_pk_add_f32 v[84:85], v[84:85], v[122:123]
	v_pk_add_f32 v[86:87], v[86:87], v[186:187]
	v_pk_add_f32 v[84:85], v[84:85], v[116:117]
	v_pk_add_f32 v[86:87], v[86:87], v[188:189]
	v_pk_add_f32 v[84:85], v[84:85], v[118:119]
	v_pk_add_f32 v[86:87], v[86:87], v[190:191]
	v_add_f32_e32 v84, v84, v85
	v_add_f32_e32 v0, v0, v86
	v_add_f32_e32 v84, v193, v84
	v_add_f32_e32 v0, v87, v0
	v_add_f32_e32 v84, v214, v84
	v_add_f32_e32 v0, v192, v0
	s_waitcnt vmcnt(0)
	s_barrier
	s_add_i32 s74, s74, 0x10000
	s_add_i32 s75, s75, 1
	v_add_f32_e32 v160, v160, v84
	v_add_f32_e32 v162, v162, v0
	v_lshl_add_u64 v[140:141], v[140:141], 0, s[4:5]
	v_lshl_add_u64 v[142:143], v[142:143], 0, s[4:5]
	v_lshl_add_u64 v[144:145], v[144:145], 0, s[34:35]
	s_cmp_lg_u32 s73, s74
	v_lshl_add_u64 v[146:147], v[146:147], 0, s[34:35]
	s_cbranch_scc0 .LBB0_417

.LBB0_420:
	v_pk_add_f32 v[84:85], v[132:133], v[134:135]
	v_pk_add_f32 v[86:87], v[2:3], v[164:165]
	v_pk_add_f32 v[84:85], v[84:85], v[194:195]
	v_pk_add_f32 v[86:87], v[86:87], v[166:167]
	v_pk_add_f32 v[84:85], v[84:85], v[206:207]
	v_pk_add_f32 v[86:87], v[86:87], v[168:169]
	v_pk_add_f32 v[84:85], v[84:85], v[208:209]
	v_pk_add_f32 v[86:87], v[86:87], v[170:171]
	v_pk_add_f32 v[84:85], v[84:85], v[210:211]
	v_pk_add_f32 v[86:87], v[86:87], v[172:173]
	v_pk_add_f32 v[84:85], v[84:85], v[212:213]
	v_pk_add_f32 v[86:87], v[86:87], v[174:175]
	v_pk_add_f32 v[84:85], v[84:85], v[128:129]
	v_pk_add_f32 v[86:87], v[86:87], v[176:177]
	v_pk_add_f32 v[84:85], v[84:85], v[130:131]
	v_pk_add_f32 v[86:87], v[86:87], v[178:179]
	v_pk_add_f32 v[84:85], v[84:85], v[124:125]
	v_pk_add_f32 v[86:87], v[86:87], v[180:181]
	v_pk_add_f32 v[84:85], v[84:85], v[126:127]
	v_pk_add_f32 v[86:87], v[86:87], v[182:183]
	v_pk_add_f32 v[84:85], v[84:85], v[120:121]
	v_pk_add_f32 v[86:87], v[86:87], v[184:185]
	v_pk_add_f32 v[84:85], v[84:85], v[122:123]
	v_pk_add_f32 v[86:87], v[86:87], v[186:187]
	v_pk_add_f32 v[84:85], v[84:85], v[116:117]
	v_pk_add_f32 v[86:87], v[86:87], v[188:189]
	v_pk_add_f32 v[84:85], v[84:85], v[118:119]
	v_pk_add_f32 v[86:87], v[86:87], v[190:191]
	v_add_f32_e32 v84, v84, v85
	v_add_f32_e32 v0, v0, v86
	v_add_f32_e32 v84, v193, v84
	v_add_f32_e32 v0, v87, v0
	v_add_f32_e32 v84, v214, v84
	v_add_f32_e32 v0, v192, v0
	s_waitcnt vmcnt(0)
	s_barrier
	s_add_i32 s55, s55, 0x10000
	s_add_i32 s56, s56, 1
	v_add_f32_e32 v160, v160, v84
	v_add_f32_e32 v162, v162, v0
	v_lshl_add_u64 v[140:141], v[140:141], 0, s[4:5]
	v_lshl_add_u64 v[142:143], v[142:143], 0, s[4:5]
	v_lshl_add_u64 v[144:145], v[144:145], 0, s[34:35]
	s_cmp_lg_u32 s25, s55
	v_lshl_add_u64 v[146:147], v[146:147], 0, s[34:35]
	s_cbranch_scc0 .LBB0_392
